# loop-edge edit: running-max carry copies moved off both attention back edges, loop closes with one taken branch
# speedup vs baseline: 1.0043x; 1.0043x over previous
; DI f4 mfma16(h8 a, h8 b, f4 c) { return __builtin_amdgcn_mfma_f32_16x16x32_f16(a, b, c, 0, 0, 0); }
; template <int DQK, bool BIAS>
; __device__ __forceinline__ void attn_pass(const hf* __restrict__ Q, int ldq, const hf* __restrict__ Kp, int ldk, const hf* __restrict__ VT,
;                                           int s0, int L, int q0, float scale_l2, const float* sBias, f4 (&oacc)[8][4], char* smem) {
;     ...
;       float ps = 0.f;
; #pragma unroll
;       for (int mk = 0; mk < 4; ++mk)
; #pragma unroll
;         for (int j = 0; j < 4; ++j) {
;           float pe = BIAS ? __builtin_amdgcn_exp2f(sacc[mk][nq][j] - mnew) : __builtin_amdgcn_exp2f(sacc[mk][nq][j] * scale_l2 - mnew);
;           sacc[mk][nq][j] = pe; ps += pe;
;         }
;       lrun[nq] += ps;
; #pragma unroll
;       for (int s2 = 0; s2 < 2; ++s2)
; #pragma unroll
;         for (int i = 0; i < 8; ++i) pf[nq][s2][i] = (hf)sacc[2 * s2 + (i >> 2)][nq][i & 3];
;     }
; #pragma unroll
;     for (int mh = 0; mh < 2; ++mh) {
;       h8 vf[4][2];
; #pragma unroll
;       for (int m4 = 0; m4 < 4; ++m4)
; #pragma unroll
;         for (int s2 = 0; s2 < 2; ++s2) {
;           h4 v0 = *(const h4*)(sVT + ((mh * 4 + m4) * 16 + fr) * 72 + s2 * 32 + fq * 4);
;           h4 v1 = *(const h4*)(sVT + ((mh * 4 + m4) * 16 + fr) * 72 + s2 * 32 + 16 + fq * 4);
;           vf[m4][s2] = __builtin_shufflevector(v0, v1, 0, 1, 2, 3, 4, 5, 6, 7);
;         }
; #pragma unroll
;       for (int nq = 0; nq < 4; ++nq)
; #pragma unroll
;         for (int m4 = 0; m4 < 4; ++m4) {
;           oacc[mh * 4 + m4][nq] = mfma16(vf[m4][0], pf[nq][0], oacc[mh * 4 + m4][nq]);
;           oacc[mh * 4 + m4][nq] = mfma16(vf[m4][1], pf[nq][1], oacc[mh * 4 + m4][nq]);
;         }
.LBB0_1976:
	v_lshlrev_b32_e32 v113, 1, v238
	v_lshlrev_b32_e32 v114, 1, v237
	v_add3_u32 v113, s95, v113, v114
	v_add_u32_e32 v114, 0x3000, v113
	ds_read2_b64 a[128:131], v114 offset0:128 offset1:132
	v_add_u32_e32 v114, 0x3000, v113
	ds_read2_b64 a[132:135], v114 offset0:136 offset1:140
	v_sub_f32_e32 v48, v128, v144
	v_exp_f32_e32 v48, v48
	v_sub_f32_e32 v50, v129, v144
	v_exp_f32_e32 v50, v50
	v_add_u32_e32 v114, 0x3800, v113
	ds_read2_b64 a[136:139], v114 offset0:160 offset1:164
	v_sub_f32_e32 v51, v130, v144
	v_exp_f32_e32 v51, v51
	v_sub_f32_e32 v52, v131, v144
	v_exp_f32_e32 v52, v52
	v_add_u32_e32 v114, 0x3800, v113
	ds_read2_b64 a[140:143], v114 offset0:168 offset1:172
	v_sub_f32_e32 v53, v140, v144
	v_add_f32_e32 v49, 0, v48
	v_exp_f32_e32 v53, v53
	v_sub_f32_e32 v54, v141, v144
	v_add_u32_e32 v114, 0x4000, v113
	ds_read2_b64 a[144:147], v114 offset0:192 offset1:196
	v_add_f32_e32 v49, v50, v49
	v_exp_f32_e32 v54, v54
	v_sub_f32_e32 v55, v142, v144
	v_add_f32_e32 v49, v51, v49
	v_add_u32_e32 v114, 0x4000, v113
	ds_read2_b64 a[148:151], v114 offset0:200 offset1:204
	v_exp_f32_e32 v55, v55
	v_sub_f32_e32 v56, v143, v144
	v_add_f32_e32 v49, v52, v49
	v_exp_f32_e32 v56, v56
	v_add_u32_e32 v114, 0x4800, v113
	ds_read2_b64 a[152:155], v114 offset0:224 offset1:228
	v_sub_f32_e32 v57, v136, v144
	v_add_f32_e32 v49, v53, v49
	v_exp_f32_e32 v57, v57
	v_sub_f32_e32 v58, v137, v144
	v_add_u32_e32 v114, 0x4800, v113
	ds_read2_b64 a[156:159], v114 offset0:232 offset1:236
	v_add_f32_e32 v49, v54, v49
	v_exp_f32_e32 v58, v58
	v_sub_f32_e32 v59, v138, v144
	v_add_f32_e32 v49, v55, v49
	v_add_u32_e32 v114, 0x5800, v113
	ds_read2_b64 a[160:163], v114 offset1:4
	v_exp_f32_e32 v59, v59
	v_sub_f32_e32 v60, v139, v144
	v_add_f32_e32 v49, v56, v49
	v_exp_f32_e32 v60, v60
	v_add_u32_e32 v114, 0x5800, v113
	ds_read2_b64 a[164:167], v114 offset0:8 offset1:12
	v_sub_f32_e32 v61, v132, v144
	v_add_f32_e32 v49, v57, v49
	v_exp_f32_e32 v61, v61
	v_sub_f32_e32 v62, v133, v144
	v_add_u32_e32 v114, 0x6000, v113
	ds_read2_b64 a[168:171], v114 offset0:32 offset1:36
	v_add_f32_e32 v49, v58, v49
	v_exp_f32_e32 v62, v62
	v_sub_f32_e32 v63, v134, v144
	v_add_f32_e32 v49, v59, v49
	v_add_u32_e32 v114, 0x6000, v113
	ds_read2_b64 a[172:175], v114 offset0:40 offset1:44
	v_exp_f32_e32 v63, v63
	v_sub_f32_e32 v64, v135, v144
	v_add_f32_e32 v49, v60, v49
	v_exp_f32_e32 v64, v64
	v_add_u32_e32 v114, 0x6800, v113
	ds_read2_b64 a[176:179], v114 offset0:64 offset1:68
	v_add_f32_e32 v49, v61, v49
	v_add_f32_e32 v49, v62, v49
	v_add_f32_e32 v49, v63, v49
	v_cvt_pk_f16_f32 v55, v55, v56
	v_add_u32_e32 v114, 0x6800, v113
	ds_read2_b64 a[180:183], v114 offset0:72 offset1:76
	v_add_f32_e32 v49, v64, v49
	v_cvt_pk_f16_f32 v54, v53, v54
	v_cvt_pk_f16_f32 v53, v51, v52
	v_cvt_pk_f16_f32 v52, v48, v50
	v_add_u32_e32 v114, 0x7000, v113
	ds_read2_b64 a[184:187], v114 offset0:96 offset1:100
	v_cvt_pk_f16_f32 v48, v57, v58
	v_add_f32_e32 v242, v49, v242
	v_cvt_pk_f16_f32 v49, v59, v60
	v_cvt_pk_f16_f32 v50, v61, v62
	v_add_u32_e32 v114, 0x7000, v113
	ds_read2_b64 a[188:191], v114 offset0:104 offset1:108
	v_cvt_pk_f16_f32 v51, v63, v64
	v_sub_f32_e32 v56, v80, v160
	v_exp_f32_e32 v56, v56
	s_waitcnt lgkmcnt(0)
	v_mfma_f32_16x16x32_f16 a[12:15], a[128:131], v[52:55], a[12:15]
	v_sub_f32_e32 v58, v81, v160
	v_exp_f32_e32 v58, v58
	v_mfma_f32_16x16x32_f16 a[28:31], a[136:139], v[52:55], a[28:31]
	v_sub_f32_e32 v59, v82, v160
	v_exp_f32_e32 v59, v59
	v_mfma_f32_16x16x32_f16 a[40:43], a[144:147], v[52:55], a[40:43]
	v_sub_f32_e32 v60, v83, v160
	v_exp_f32_e32 v60, v60
	v_mfma_f32_16x16x32_f16 a[56:59], a[152:155], v[52:55], a[56:59]
	v_sub_f32_e32 v61, v92, v160
	v_add_f32_e32 v57, 0, v56
	v_mfma_f32_16x16x32_f16 a[12:15], a[132:135], v[48:51], a[12:15]
	v_exp_f32_e32 v61, v61
	v_sub_f32_e32 v62, v93, v160
	v_mfma_f32_16x16x32_f16 a[28:31], a[140:143], v[48:51], a[28:31]
	v_add_f32_e32 v57, v58, v57
	v_exp_f32_e32 v62, v62
	v_mfma_f32_16x16x32_f16 a[40:43], a[148:151], v[48:51], a[40:43]
	v_sub_f32_e32 v63, v94, v160
	v_add_f32_e32 v57, v59, v57
	v_mfma_f32_16x16x32_f16 a[56:59], a[156:159], v[48:51], a[56:59]
	v_exp_f32_e32 v63, v63
	v_sub_f32_e32 v64, v95, v160
	v_mfma_f32_16x16x32_f16 a[72:75], a[160:163], v[52:55], a[72:75]
	v_sub_f32_e32 v32, v32, v176
	v_add_f32_e32 v57, v60, v57
	v_mfma_f32_16x16x32_f16 a[88:91], a[168:171], v[52:55], a[88:91]
	v_exp_f32_e32 v64, v64
	v_exp_f32_e32 v32, v32
	v_mfma_f32_16x16x32_f16 a[108:111], a[176:179], v[52:55], a[108:111]
	v_sub_f32_e32 v33, v33, v176
	v_add_f32_e32 v57, v61, v57
	v_mfma_f32_16x16x32_f16 a[120:123], a[184:187], v[52:55], a[120:123]
	v_exp_f32_e32 v33, v33
	v_sub_f32_e32 v34, v34, v176
	v_mfma_f32_16x16x32_f16 a[72:75], a[164:167], v[48:51], a[72:75]
	v_add_f32_e32 v57, v62, v57
	v_exp_f32_e32 v34, v34
	v_mfma_f32_16x16x32_f16 a[88:91], a[172:175], v[48:51], a[88:91]
	v_sub_f32_e32 v35, v35, v176
	v_add_f32_e32 v57, v63, v57
	v_mfma_f32_16x16x32_f16 a[108:111], a[180:183], v[48:51], a[108:111]
	v_exp_f32_e32 v35, v35
	v_sub_f32_e32 v44, v44, v176
	v_mfma_f32_16x16x32_f16 a[120:123], a[188:191], v[48:51], a[120:123]
	v_add_f32_e32 v57, v64, v57
	v_sub_f32_e32 v65, v84, v160
	v_sub_f32_e32 v66, v85, v160
	v_cvt_pk_f16_f32 v63, v63, v64
	v_add_f32_e32 v64, 0, v32
	v_exp_f32_e32 v44, v44
	v_sub_f32_e32 v45, v45, v176
	v_exp_f32_e32 v65, v65
	v_exp_f32_e32 v66, v66
	v_add_f32_e32 v64, v33, v64
	v_exp_f32_e32 v45, v45
	v_sub_f32_e32 v46, v46, v176
	v_add_f32_e32 v64, v34, v64
	v_exp_f32_e32 v46, v46
	v_sub_f32_e32 v47, v47, v176
	v_add_f32_e32 v64, v35, v64
	v_exp_f32_e32 v47, v47
	v_sub_f32_e32 v40, v40, v176
	v_add_f32_e32 v64, v44, v64
; DI f4 mfma16(h8 a, h8 b, f4 c) { return __builtin_amdgcn_mfma_f32_16x16x32_f16(a, b, c, 0, 0, 0); }
; template <int DQK, bool BIAS>
; __device__ __forceinline__ void attn_pass(const hf* __restrict__ Q, int ldq, const hf* __restrict__ Kp, int ldk, const hf* __restrict__ VT,
;                                           int s0, int L, int q0, float scale_l2, const float* sBias, f4 (&oacc)[8][4], char* smem) {
;     ...
;       float ps = 0.f;
; #pragma unroll
;       for (int mk = 0; mk < 4; ++mk)
; #pragma unroll
;         for (int j = 0; j < 4; ++j) {
;           float pe = BIAS ? __builtin_amdgcn_exp2f(sacc[mk][nq][j] - mnew) : __builtin_amdgcn_exp2f(sacc[mk][nq][j] * scale_l2 - mnew);
;           sacc[mk][nq][j] = pe; ps += pe;
;         }
;       lrun[nq] += ps;
; #pragma unroll
;       for (int s2 = 0; s2 < 2; ++s2)
; #pragma unroll
;         for (int i = 0; i < 8; ++i) pf[nq][s2][i] = (hf)sacc[2 * s2 + (i >> 2)][nq][i & 3];
;     }
; #pragma unroll
;     for (int mh = 0; mh < 2; ++mh) {
;       h8 vf[4][2];
; #pragma unroll
;       for (int m4 = 0; m4 < 4; ++m4)
; #pragma unroll
;         for (int s2 = 0; s2 < 2; ++s2) {
;           h4 v0 = *(const h4*)(sVT + ((mh * 4 + m4) * 16 + fr) * 72 + s2 * 32 + fq * 4);
;           h4 v1 = *(const h4*)(sVT + ((mh * 4 + m4) * 16 + fr) * 72 + s2 * 32 + 16 + fq * 4);
;           vf[m4][s2] = __builtin_shufflevector(v0, v1, 0, 1, 2, 3, 4, 5, 6, 7);
;         }
; #pragma unroll
;       for (int nq = 0; nq < 4; ++nq)
; #pragma unroll
;         for (int m4 = 0; m4 < 4; ++m4) {
;           oacc[mh * 4 + m4][nq] = mfma16(vf[m4][0], pf[nq][0], oacc[mh * 4 + m4][nq]);
;           oacc[mh * 4 + m4][nq] = mfma16(vf[m4][1], pf[nq][1], oacc[mh * 4 + m4][nq]);
;         }
;     }
;     __syncthreads();
	v_exp_f32_e32 v40, v40
	v_sub_f32_e32 v41, v41, v176
	v_add_f32_e32 v57, v65, v57
	v_cvt_pk_f16_f32 v62, v61, v62
	v_cvt_pk_f16_f32 v61, v59, v60
	v_cvt_pk_f16_f32 v60, v56, v58
	v_cvt_pk_f16_f32 v56, v65, v66
	v_add_f32_e32 v64, v45, v64
	v_exp_f32_e32 v65, v41
	v_add_f32_e32 v64, v46, v64
	v_add_f32_e32 v64, v47, v64
	v_add_f32_e32 v64, v40, v64
	v_sub_f32_e32 v42, v42, v176
	v_add_f32_e32 v41, v65, v64
	v_exp_f32_e32 v64, v42
	v_sub_f32_e32 v42, v43, v176
	v_add_f32_e32 v57, v66, v57
	v_exp_f32_e32 v66, v42
	v_sub_f32_e32 v36, v36, v176
	v_sub_f32_e32 v37, v37, v176
	v_exp_f32_e32 v36, v36
	v_exp_f32_e32 v37, v37
	v_sub_f32_e32 v38, v38, v176
	v_sub_f32_e32 v39, v39, v176
	v_cvt_pk_f16_f32 v47, v46, v47
	v_cvt_pk_f16_f32 v46, v44, v45
	v_cvt_pk_f16_f32 v44, v32, v33
	v_add_f32_e32 v41, v64, v41
	v_exp_f32_e32 v38, v38
	v_exp_f32_e32 v39, v39
	v_cvt_pk_f16_f32 v45, v34, v35
	v_add_f32_e32 v41, v66, v41
	v_add_f32_e32 v41, v36, v41
	v_cvt_pk_f16_f32 v42, v36, v37
	v_add_f32_e32 v41, v37, v41
	v_add_f32_e32 v41, v38, v41
	v_cvt_pk_f16_f32 v43, v38, v39
	v_add_f32_e32 v41, v39, v41
	v_add_f32_e32 v245, v41, v245
	v_cvt_pk_f16_f32 v41, v64, v66
	v_cvt_pk_f16_f32 v40, v40, v65
	v_sub_f32_e32 v67, v86, v160
	v_exp_f32_e32 v67, v67
	v_mfma_f32_16x16x32_f16 a[0:3], a[128:131], v[44:47], a[0:3]
	v_sub_f32_e32 v68, v87, v160
	v_exp_f32_e32 v68, v68
	v_mfma_f32_16x16x32_f16 a[8:11], a[136:139], v[44:47], a[8:11]
	v_sub_f32_e32 v69, v88, v160
	v_exp_f32_e32 v69, v69
	v_mfma_f32_16x16x32_f16 a[24:27], a[144:147], v[44:47], a[24:27]
	v_sub_f32_e32 v70, v89, v160
	v_exp_f32_e32 v70, v70
	v_mfma_f32_16x16x32_f16 a[44:47], a[152:155], v[44:47], a[44:47]
	v_sub_f32_e32 v71, v90, v160
	v_add_f32_e32 v57, v67, v57
	v_mfma_f32_16x16x32_f16 a[0:3], a[132:135], v[40:43], a[0:3]
	v_exp_f32_e32 v71, v71
	v_sub_f32_e32 v72, v91, v160
	v_mfma_f32_16x16x32_f16 a[8:11], a[140:143], v[40:43], a[8:11]
	v_add_f32_e32 v57, v68, v57
	v_exp_f32_e32 v72, v72
	v_mfma_f32_16x16x32_f16 a[24:27], a[148:151], v[40:43], a[24:27]
	v_add_f32_e32 v57, v69, v57
	v_add_f32_e32 v57, v70, v57
	v_mfma_f32_16x16x32_f16 a[44:47], a[156:159], v[40:43], a[44:47]
	v_add_f32_e32 v57, v71, v57
	v_add_f32_e32 v57, v72, v57
	v_mfma_f32_16x16x32_f16 a[64:67], a[160:163], v[44:47], a[64:67]
	v_add_f32_e32 v243, v57, v243
	v_cvt_pk_f16_f32 v57, v67, v68
	v_mfma_f32_16x16x32_f16 a[76:79], a[168:171], v[44:47], a[76:79]
	v_cvt_pk_f16_f32 v58, v69, v70
	v_cvt_pk_f16_f32 v59, v71, v72
	v_mfma_f32_16x16x32_f16 a[92:95], a[176:179], v[44:47], a[92:95]
	v_sub_f32_e32 v32, v96, v112
	v_exp_f32_e32 v32, v32
	v_mfma_f32_16x16x32_f16 a[104:107], a[184:187], v[44:47], a[104:107]
	v_sub_f32_e32 v34, v97, v112
	v_exp_f32_e32 v34, v34
	v_mfma_f32_16x16x32_f16 a[64:67], a[164:167], v[40:43], a[64:67]
	v_sub_f32_e32 v35, v98, v112
	v_exp_f32_e32 v35, v35
	v_mfma_f32_16x16x32_f16 a[76:79], a[172:175], v[40:43], a[76:79]
	v_sub_f32_e32 v36, v99, v112
	v_exp_f32_e32 v36, v36
	v_mfma_f32_16x16x32_f16 a[92:95], a[180:183], v[40:43], a[92:95]
	v_sub_f32_e32 v37, v104, v112
	v_add_f32_e32 v33, 0, v32
	v_mfma_f32_16x16x32_f16 a[104:107], a[188:191], v[40:43], a[104:107]
	v_exp_f32_e32 v37, v37
	v_sub_f32_e32 v38, v105, v112
	v_mfma_f32_16x16x32_f16 a[4:7], a[128:131], v[60:63], a[4:7]
	v_add_f32_e32 v33, v34, v33
	v_exp_f32_e32 v38, v38
	v_mfma_f32_16x16x32_f16 a[16:19], a[136:139], v[60:63], a[16:19]
	v_sub_f32_e32 v39, v106, v112
	v_add_f32_e32 v33, v35, v33
	v_mfma_f32_16x16x32_f16 a[36:39], a[144:147], v[60:63], a[36:39]
	v_exp_f32_e32 v39, v39
	v_sub_f32_e32 v64, v107, v112
	v_mfma_f32_16x16x32_f16 a[52:55], a[152:155], v[60:63], a[52:55]
	v_add_f32_e32 v33, v36, v33
	v_exp_f32_e32 v64, v64
	v_mfma_f32_16x16x32_f16 a[4:7], a[132:135], v[56:59], a[4:7]
	v_sub_f32_e32 v65, v100, v112
	v_add_f32_e32 v33, v37, v33
	v_mfma_f32_16x16x32_f16 a[16:19], a[140:143], v[56:59], a[16:19]
	v_exp_f32_e32 v65, v65
	v_sub_f32_e32 v66, v101, v112
	v_mfma_f32_16x16x32_f16 a[36:39], a[148:151], v[56:59], a[36:39]
	v_add_f32_e32 v33, v38, v33
	v_exp_f32_e32 v66, v66
	v_mfma_f32_16x16x32_f16 a[52:55], a[156:159], v[56:59], a[52:55]
	v_sub_f32_e32 v67, v102, v112
	v_add_f32_e32 v33, v39, v33
	v_mfma_f32_16x16x32_f16 a[68:71], a[160:163], v[60:63], a[68:71]
	v_exp_f32_e32 v67, v67
	v_sub_f32_e32 v68, v103, v112
	v_mfma_f32_16x16x32_f16 a[84:87], a[168:171], v[60:63], a[84:87]
	v_add_f32_e32 v33, v64, v33
	v_exp_f32_e32 v68, v68
	v_mfma_f32_16x16x32_f16 a[100:103], a[176:179], v[60:63], a[100:103]
	v_sub_f32_e32 v69, v108, v112
	v_add_f32_e32 v33, v65, v33
	v_mfma_f32_16x16x32_f16 a[116:119], a[184:187], v[60:63], a[116:119]
	v_exp_f32_e32 v69, v69
	v_sub_f32_e32 v70, v109, v112
	v_mfma_f32_16x16x32_f16 a[68:71], a[164:167], v[56:59], a[68:71]
	v_add_f32_e32 v33, v66, v33
	v_exp_f32_e32 v70, v70
	v_mfma_f32_16x16x32_f16 a[84:87], a[172:175], v[56:59], a[84:87]
	v_sub_f32_e32 v71, v110, v112
	v_add_f32_e32 v33, v67, v33
	v_mfma_f32_16x16x32_f16 a[100:103], a[180:183], v[56:59], a[100:103]
	v_exp_f32_e32 v71, v71
	v_sub_f32_e32 v72, v111, v112
	v_mfma_f32_16x16x32_f16 a[116:119], a[188:191], v[56:59], a[116:119]
	v_add_f32_e32 v33, v68, v33
	v_exp_f32_e32 v72, v72
	v_add_f32_e32 v33, v69, v33
	v_add_f32_e32 v33, v70, v33
	v_cvt_pk_f16_f32 v39, v39, v64
	v_cvt_pk_f16_f32 v38, v37, v38
	v_cvt_pk_f16_f32 v37, v35, v36
	v_cvt_pk_f16_f32 v36, v32, v34
	v_cvt_pk_f16_f32 v32, v65, v66
	v_add_f32_e32 v33, v71, v33
	v_add_f32_e32 v33, v72, v33
	v_add_f32_e32 v233, v33, v233
	v_cvt_pk_f16_f32 v35, v71, v72
	v_cvt_pk_f16_f32 v34, v69, v70
	v_cvt_pk_f16_f32 v33, v67, v68
	s_nop 1
	s_waitcnt lgkmcnt(0)
	s_barrier
; DI f4 mfma16(h8 a, h8 b, f4 c) { return __builtin_amdgcn_mfma_f32_16x16x32_f16(a, b, c, 0, 0, 0); }
; template <int DQK, bool BIAS>
; __device__ __forceinline__ void attn_pass(const hf* __restrict__ Q, int ldq, const hf* __restrict__ Kp, int ldk, const hf* __restrict__ VT,
;                                           int s0, int L, int q0, float scale_l2, const float* sBias, f4 (&oacc)[8][4], char* smem) {
;     ...
;   for (int kt = 0; kt < nkt; ++kt) {
;     const hf* sK = sbase + (kt & 1) * A_STG; const hf* sVT = sK + 64 * 104;
;     f4 sacc[4][4];
; #pragma unroll
;     for (int mk = 0; mk < 4; ++mk) {
;       h8 kf[NKS];
; #pragma unroll
;       for (int ks = 0; ks < NKS; ++ks) kf[ks] = *(const h8*)(sK + (mk * 16 + fr) * KS + ks * 32 + (fq ^ (((fr >> 2) ^ (fr >> 3)) & 1)) * 8);
;     ...
;       for (int nq = 0; nq < 4; ++nq)
; #pragma unroll
;         for (int m4 = 0; m4 < 4; ++m4) {
;           oacc[mh * 4 + m4][nq] = mfma16(vf[m4][0], pf[nq][0], oacc[mh * 4 + m4][nq]);
;           oacc[mh * 4 + m4][nq] = mfma16(vf[m4][1], pf[nq][1], oacc[mh * 4 + m4][nq]);
;         }
;     }
;     __syncthreads();
	s_bitcmp1_b32 s94, 0
	s_cselect_b32 s26, 0x7c00, 0
	s_add_i32 s26, s26, 16
	v_add_u32_e32 v113, s26, v239
	v_lshl_add_u32 v114, v238, 1, v113
	v_add_u32_e32 v113, v113, v240
	ds_read_b128 v[72:75], v114
	ds_read_b128 v[76:79], v114 offset:64
	ds_read_b128 v[48:51], v113 offset:2304
	ds_read_b128 v[52:55], v113 offset:2368
	ds_read_b128 v[56:59], v113 offset:4608
	ds_read_b128 v[60:63], v113 offset:4672
	ds_read_b128 v[40:43], v113 offset:6912
	ds_read_b128 v[64:67], v113 offset:6976
	v_mov_b32_e32 v246, v112
	v_mov_b32_e32 v247, v144
	v_mov_b32_e32 v253, v160
	v_mov_b32_e32 v198, v176
	v_mfma_f32_16x16x32_f16 a[20:23], a[128:131], v[36:39], a[20:23]
	v_mfma_f32_16x16x32_f16 a[32:35], a[136:139], v[36:39], a[32:35]
	v_mfma_f32_16x16x32_f16 a[48:51], a[144:147], v[36:39], a[48:51]
	v_mfma_f32_16x16x32_f16 a[60:63], a[152:155], v[36:39], a[60:63]
	v_mfma_f32_16x16x32_f16 a[20:23], a[132:135], v[32:35], a[20:23]
	v_mfma_f32_16x16x32_f16 a[32:35], a[140:143], v[32:35], a[32:35]
	v_mfma_f32_16x16x32_f16 a[48:51], a[148:151], v[32:35], a[48:51]
	v_mfma_f32_16x16x32_f16 a[60:63], a[156:159], v[32:35], a[60:63]
	v_mfma_f32_16x16x32_f16 a[80:83], a[160:163], v[36:39], a[80:83]
	v_mfma_f32_16x16x32_f16 a[96:99], a[168:171], v[36:39], a[96:99]
	v_mfma_f32_16x16x32_f16 a[112:115], a[176:179], v[36:39], a[112:115]
	v_mfma_f32_16x16x32_f16 a[124:127], a[184:187], v[36:39], a[124:127]
	v_mfma_f32_16x16x32_f16 a[80:83], a[164:167], v[32:35], a[80:83]
	v_mfma_f32_16x16x32_f16 a[96:99], a[172:175], v[32:35], a[96:99]
	v_mfma_f32_16x16x32_f16 a[112:115], a[180:183], v[32:35], a[112:115]
	v_mfma_f32_16x16x32_f16 a[124:127], a[188:191], v[32:35], a[124:127]
	s_mov_b32 s16, s94
	s_add_i32 s20, s20, 64
	s_cmp_lg_u32 s73, s94
	s_cbranch_scc1 .LBB0_1948
	s_branch .LBB0_1978

; DI f4 mfma16(h8 a, h8 b, f4 c) { return __builtin_amdgcn_mfma_f32_16x16x32_f16(a, b, c, 0, 0, 0); }
; template <int DQK, bool BIAS>
; __device__ __forceinline__ void attn_pass(const hf* __restrict__ Q, int ldq, const hf* __restrict__ Kp, int ldk, const hf* __restrict__ VT,
;                                           int s0, int L, int q0, float scale_l2, const float* sBias, f4 (&oacc)[8][4], char* smem) {
;     ...
;       float ps = 0.f;
; #pragma unroll
;       for (int mk = 0; mk < 4; ++mk)
; #pragma unroll
;         for (int j = 0; j < 4; ++j) {
;           float pe = BIAS ? __builtin_amdgcn_exp2f(sacc[mk][nq][j] - mnew) : __builtin_amdgcn_exp2f(sacc[mk][nq][j] * scale_l2 - mnew);
;           sacc[mk][nq][j] = pe; ps += pe;
;         }
;       lrun[nq] += ps;
; #pragma unroll
;       for (int s2 = 0; s2 < 2; ++s2)
; #pragma unroll
;         for (int i = 0; i < 8; ++i) pf[nq][s2][i] = (hf)sacc[2 * s2 + (i >> 2)][nq][i & 3];
;     }
; #pragma unroll
;     for (int mh = 0; mh < 2; ++mh) {
;       h8 vf[4][2];
; #pragma unroll
;       for (int m4 = 0; m4 < 4; ++m4)
; #pragma unroll
;         for (int s2 = 0; s2 < 2; ++s2) {
;           h4 v0 = *(const h4*)(sVT + ((mh * 4 + m4) * 16 + fr) * 72 + s2 * 32 + fq * 4);
;           h4 v1 = *(const h4*)(sVT + ((mh * 4 + m4) * 16 + fr) * 72 + s2 * 32 + 16 + fq * 4);
;           vf[m4][s2] = __builtin_shufflevector(v0, v1, 0, 1, 2, 3, 4, 5, 6, 7);
;         }
; #pragma unroll
;       for (int nq = 0; nq < 4; ++nq)
; #pragma unroll
;         for (int m4 = 0; m4 < 4; ++m4) {
;           oacc[mh * 4 + m4][nq] = mfma16(vf[m4][0], pf[nq][0], oacc[mh * 4 + m4][nq]);
;           oacc[mh * 4 + m4][nq] = mfma16(vf[m4][1], pf[nq][1], oacc[mh * 4 + m4][nq]);
;         }
.Lmla_slow_3:
.LBB0_2006:
	v_fma_f32 v52, v188, s26, -v192
	v_exp_f32_e32 v112, v52
	v_fma_f32 v52, v189, s26, -v192
	v_exp_f32_e32 v113, v52
	v_fma_f32 v52, v190, s26, -v192
	v_exp_f32_e32 v114, v52
	v_fma_f32 v52, v68, s26, -v241
	v_exp_f32_e32 v115, v52
	v_fma_f32 v52, v69, s26, -v241
	v_exp_f32_e32 v116, v52
	v_fma_f32 v52, v70, s26, -v241
	v_exp_f32_e32 v117, v52
	v_fma_f32 v52, v71, s26, -v241
	v_exp_f32_e32 v118, v52
	v_fma_f32 v52, v204, s26, -v241
	v_fma_f32 v72, v72, s26, -v192
	v_exp_f32_e32 v119, v52
	v_fma_f32 v52, v205, s26, -v241
	v_exp_f32_e32 v108, v72
	v_fma_f32 v72, v73, s26, -v192
	v_exp_f32_e32 v120, v52
	v_fma_f32 v52, v206, s26, -v241
	v_exp_f32_e32 v109, v72
	v_fma_f32 v72, v74, s26, -v192
	v_exp_f32_e32 v121, v52
	v_fma_f32 v52, v207, s26, -v241
	v_exp_f32_e32 v110, v72
	v_fma_f32 v72, v75, s26, -v192
	v_exp_f32_e32 v122, v52
	v_fma_f32 v52, v200, s26, -v241
	v_exp_f32_e32 v111, v72
	v_exp_f32_e32 v123, v52
	v_fma_f32 v52, v201, s26, -v241
	v_fma_f32 v72, v124, s26, -v128
	v_exp_f32_e32 v129, v52
	v_fma_f32 v52, v202, s26, -v241
	v_exp_f32_e32 v124, v72
	v_fma_f32 v72, v125, s26, -v128
	v_exp_f32_e32 v130, v52
	v_fma_f32 v52, v203, s26, -v241
	v_exp_f32_e32 v125, v72
	v_fma_f32 v72, v126, s26, -v128
	v_exp_f32_e32 v131, v52
	v_fma_f32 v52, v196, s26, -v241
	v_exp_f32_e32 v126, v72
	v_fma_f32 v72, v127, s26, -v128
	v_exp_f32_e32 v132, v52
	v_fma_f32 v52, v197, s26, -v241
	v_exp_f32_e32 v127, v72
	v_fma_f32 v72, v104, s26, -v128
	v_exp_f32_e32 v133, v52
	v_fma_f32 v52, v198, s26, -v241
	v_exp_f32_e32 v104, v72
	v_fma_f32 v72, v105, s26, -v128
	v_exp_f32_e32 v134, v52
	v_fma_f32 v52, v199, s26, -v241
	v_add3_u32 v136, s15, v234, v239
	v_exp_f32_e32 v105, v72
	v_fma_f32 v72, v106, s26, -v128
	v_exp_f32_e32 v135, v52
	v_add_u32_e32 v52, 0x3000, v136
	v_exp_f32_e32 v106, v72
	v_fma_f32 v72, v107, s26, -v128
	ds_read2_b64 v[146:149], v52 offset0:128 offset1:132
	ds_read2_b64 v[150:153], v52 offset0:136 offset1:140
	v_add_u32_e32 v52, 0x3800, v136
	v_exp_f32_e32 v107, v72
	v_fma_f32 v72, v84, s26, -v128
	ds_read2_b64 v[154:157], v52 offset0:160 offset1:164
	v_add_u32_e32 v53, 0x4000, v136
	v_exp_f32_e32 v84, v72
	v_fma_f32 v72, v85, s26, -v128
	v_fma_f32 v96, v164, s26, -v176
	v_fma_f32 v97, v165, s26, -v176
	v_fma_f32 v102, v162, s26, -v176
	v_fma_f32 v103, v163, s26, -v176
	ds_read2_b64 v[162:165], v53 offset0:192 offset1:196
	v_exp_f32_e32 v85, v72
	v_fma_f32 v72, v86, s26, -v128
	v_fma_f32 v88, v172, s26, -v176
	v_fma_f32 v89, v173, s26, -v176
	v_fma_f32 v90, v174, s26, -v176
	v_fma_f32 v91, v175, s26, -v176
	v_fma_f32 v92, v168, s26, -v176
	v_fma_f32 v93, v169, s26, -v176
	v_fma_f32 v94, v170, s26, -v176
	v_fma_f32 v95, v171, s26, -v176
	v_fma_f32 v80, v80, s26, -v192
	v_fma_f32 v81, v81, s26, -v192
	v_fma_f32 v82, v82, s26, -v192
	v_fma_f32 v83, v83, s26, -v192
	v_exp_f32_e32 v86, v72
	v_fma_f32 v72, v87, s26, -v128
	v_exp_f32_e32 v88, v88
	v_exp_f32_e32 v89, v89
	v_exp_f32_e32 v90, v90
	v_exp_f32_e32 v91, v91
	v_exp_f32_e32 v92, v92
	v_exp_f32_e32 v93, v93
	v_exp_f32_e32 v94, v94
	v_exp_f32_e32 v95, v95
	v_exp_f32_e32 v80, v80
	v_exp_f32_e32 v81, v81
	v_exp_f32_e32 v82, v82
	v_exp_f32_e32 v83, v83
	v_fma_f32 v48, v184, s26, -v192
	v_exp_f32_e32 v87, v72
	v_fma_f32 v72, v76, s26, -v128
	v_fma_f32 v100, v160, s26, -v176
	v_fma_f32 v101, v161, s26, -v176
	ds_read2_b64 v[158:161], v52 offset0:168 offset1:172
	v_exp_f32_e32 v138, v48
	v_add_u32_e32 v48, 0x4800, v136
	v_exp_f32_e32 v142, v72
	v_fma_f32 v72, v77, s26, -v128
	v_fma_f32 v98, v166, s26, -v176
	v_fma_f32 v99, v167, s26, -v176
	ds_read2_b64 v[166:169], v53 offset0:200 offset1:204
	ds_read2_b64 v[170:173], v48 offset0:224 offset1:228
	ds_read2_b64 v[178:181], v48 offset0:232 offset1:236
	v_fma_f32 v48, v186, s26, -v192
	v_exp_f32_e32 v143, v72
	v_fma_f32 v72, v78, s26, -v128
	v_fma_f32 v52, v191, s26, -v192
	v_fma_f32 v49, v185, s26, -v192
	v_exp_f32_e32 v140, v48
	v_fma_f32 v48, v187, s26, -v192
	v_exp_f32_e32 v144, v72
	v_fma_f32 v72, v79, s26, -v128
	v_exp_f32_e32 v96, v96
	v_exp_f32_e32 v97, v97
	v_exp_f32_e32 v98, v98
	v_exp_f32_e32 v99, v99
	v_exp_f32_e32 v100, v100
	v_exp_f32_e32 v101, v101
	v_exp_f32_e32 v102, v102
	v_exp_f32_e32 v103, v103
	v_cvt_pk_f16_f32 v59, v121, v122
	v_cvt_pk_f16_f32 v58, v119, v120
	v_cvt_pk_f16_f32 v57, v117, v118
	v_cvt_pk_f16_f32 v56, v115, v116
	v_exp_f32_e32 v137, v52
	v_exp_f32_e32 v139, v49
	v_exp_f32_e32 v141, v48
	v_cvt_pk_f16_f32 v51, v110, v111
	v_cvt_pk_f16_f32 v50, v108, v109
	v_cvt_pk_f16_f32 v49, v82, v83
	v_cvt_pk_f16_f32 v48, v80, v81
	v_cvt_pk_f16_f32 v67, v94, v95
	v_cvt_pk_f16_f32 v66, v92, v93
	v_cvt_pk_f16_f32 v65, v90, v91
	v_cvt_pk_f16_f32 v64, v88, v89
	v_exp_f32_e32 v145, v72
	v_cvt_pk_f16_f32 v75, v106, v107
	v_cvt_pk_f16_f32 v74, v104, v105
	v_cvt_pk_f16_f32 v73, v126, v127
	v_cvt_pk_f16_f32 v72, v124, v125
	s_waitcnt lgkmcnt(7)
	v_mfma_f32_16x16x32_f16 a[0:3], v[146:149], v[56:59], a[0:3]
	v_cvt_pk_f16_f32 v63, v134, v135
	v_cvt_pk_f16_f32 v62, v132, v133
	v_cvt_pk_f16_f32 v61, v130, v131
	v_mfma_f32_16x16x32_f16 a[4:7], v[146:149], v[48:51], a[4:7]
	v_cvt_pk_f16_f32 v60, v123, v129
	v_cvt_pk_f16_f32 v55, v140, v141
	v_cvt_pk_f16_f32 v54, v138, v139
	v_mfma_f32_16x16x32_f16 a[12:15], v[146:149], v[64:67], a[12:15]
	v_cvt_pk_f16_f32 v53, v114, v137
	v_cvt_pk_f16_f32 v52, v112, v113
	v_cvt_pk_f16_f32 v71, v102, v103
	v_mfma_f32_16x16x32_f16 a[20:23], v[146:149], v[72:75], a[20:23]
	v_cvt_pk_f16_f32 v70, v100, v101
	v_cvt_pk_f16_f32 v69, v98, v99
	v_cvt_pk_f16_f32 v68, v96, v97
	s_waitcnt lgkmcnt(5)
; DI f4 mfma16(h8 a, h8 b, f4 c) { return __builtin_amdgcn_mfma_f32_16x16x32_f16(a, b, c, 0, 0, 0); }
; template <int DQK, bool BIAS>
; __device__ __forceinline__ void attn_pass(const hf* __restrict__ Q, int ldq, const hf* __restrict__ Kp, int ldk, const hf* __restrict__ VT,
;                                           int s0, int L, int q0, float scale_l2, const float* sBias, f4 (&oacc)[8][4], char* smem) {
;     ...
;       float ps = 0.f;
; #pragma unroll
;       for (int mk = 0; mk < 4; ++mk)
; #pragma unroll
;         for (int j = 0; j < 4; ++j) {
;           float pe = BIAS ? __builtin_amdgcn_exp2f(sacc[mk][nq][j] - mnew) : __builtin_amdgcn_exp2f(sacc[mk][nq][j] * scale_l2 - mnew);
;           sacc[mk][nq][j] = pe; ps += pe;
;         }
;       lrun[nq] += ps;
; #pragma unroll
;       for (int s2 = 0; s2 < 2; ++s2)
; #pragma unroll
;         for (int i = 0; i < 8; ++i) pf[nq][s2][i] = (hf)sacc[2 * s2 + (i >> 2)][nq][i & 3];
;     }
; #pragma unroll
;     for (int mh = 0; mh < 2; ++mh) {
;       h8 vf[4][2];
; #pragma unroll
;       for (int m4 = 0; m4 < 4; ++m4)
; #pragma unroll
;         for (int s2 = 0; s2 < 2; ++s2) {
;           h4 v0 = *(const h4*)(sVT + ((mh * 4 + m4) * 16 + fr) * 72 + s2 * 32 + fq * 4);
;           h4 v1 = *(const h4*)(sVT + ((mh * 4 + m4) * 16 + fr) * 72 + s2 * 32 + 16 + fq * 4);
;           vf[m4][s2] = __builtin_shufflevector(v0, v1, 0, 1, 2, 3, 4, 5, 6, 7);
;         }
; #pragma unroll
;       for (int nq = 0; nq < 4; ++nq)
; #pragma unroll
;         for (int m4 = 0; m4 < 4; ++m4) {
;           oacc[mh * 4 + m4][nq] = mfma16(vf[m4][0], pf[nq][0], oacc[mh * 4 + m4][nq]);
;           oacc[mh * 4 + m4][nq] = mfma16(vf[m4][1], pf[nq][1], oacc[mh * 4 + m4][nq]);
;         }
;     }
;     __syncthreads();
	v_mfma_f32_16x16x32_f16 a[8:11], v[154:157], v[56:59], a[8:11]
	v_cvt_pk_f16_f32 v79, v144, v145
	v_cvt_pk_f16_f32 v78, v142, v143
	v_cvt_pk_f16_f32 v77, v86, v87
	v_mfma_f32_16x16x32_f16 a[16:19], v[154:157], v[48:51], a[16:19]
	v_cvt_pk_f16_f32 v76, v84, v85
	v_add_u32_e32 v146, 0x5800, v136
	s_add_i32 s12, s12, 64
	v_mfma_f32_16x16x32_f16 a[24:27], v[154:157], v[64:67], a[24:27]
	s_cmp_lg_u32 s18, s14
	v_mfma_f32_16x16x32_f16 a[36:39], v[154:157], v[72:75], a[36:39]
	s_waitcnt lgkmcnt(4)
	v_mfma_f32_16x16x32_f16 a[28:31], v[162:165], v[56:59], a[28:31]
	v_mfma_f32_16x16x32_f16 a[32:35], v[162:165], v[48:51], a[32:35]
	v_mfma_f32_16x16x32_f16 a[44:47], v[162:165], v[64:67], a[44:47]
	v_mfma_f32_16x16x32_f16 a[52:55], v[162:165], v[72:75], a[52:55]
	v_mfma_f32_16x16x32_f16 a[0:3], v[150:153], v[60:63], a[0:3]
	v_mfma_f32_16x16x32_f16 a[4:7], v[150:153], v[52:55], a[4:7]
	v_mfma_f32_16x16x32_f16 a[12:15], v[150:153], v[68:71], a[12:15]
	v_mfma_f32_16x16x32_f16 a[20:23], v[150:153], v[76:79], a[20:23]
	ds_read2_b64 v[148:151], v146 offset1:4
	ds_read2_b64 v[152:155], v146 offset0:8 offset1:12
	v_add_u32_e32 v146, 0x6000, v136
	s_waitcnt lgkmcnt(5)
	v_mfma_f32_16x16x32_f16 a[8:11], v[158:161], v[60:63], a[8:11]
	v_mfma_f32_16x16x32_f16 a[16:19], v[158:161], v[52:55], a[16:19]
	v_mfma_f32_16x16x32_f16 a[24:27], v[158:161], v[68:71], a[24:27]
	v_mfma_f32_16x16x32_f16 a[36:39], v[158:161], v[76:79], a[36:39]
	ds_read2_b64 v[156:159], v146 offset0:32 offset1:36
	ds_read2_b64 v[160:163], v146 offset0:40 offset1:44
	v_add_u32_e32 v146, 0x6800, v136
	v_add_u32_e32 v136, 0x7000, v136
	s_waitcnt lgkmcnt(6)
	v_mfma_f32_16x16x32_f16 a[28:31], v[166:169], v[60:63], a[28:31]
	s_waitcnt lgkmcnt(5)
	v_mfma_f32_16x16x32_f16 a[40:43], v[170:173], v[56:59], a[40:43]
	v_mfma_f32_16x16x32_f16 a[32:35], v[166:169], v[52:55], a[32:35]
	v_mfma_f32_16x16x32_f16 a[48:51], v[170:173], v[48:51], a[48:51]
	v_mfma_f32_16x16x32_f16 a[44:47], v[166:169], v[68:71], a[44:47]
	v_mfma_f32_16x16x32_f16 a[56:59], v[170:173], v[64:67], a[56:59]
	v_mfma_f32_16x16x32_f16 a[52:55], v[166:169], v[76:79], a[52:55]
	ds_read2_b64 v[164:167], v146 offset0:64 offset1:68
	v_mfma_f32_16x16x32_f16 a[60:63], v[170:173], v[72:75], a[60:63]
	ds_read2_b64 v[172:175], v136 offset0:96 offset1:100
	ds_read2_b64 v[168:171], v146 offset0:72 offset1:76
	s_waitcnt lgkmcnt(6)
	v_mfma_f32_16x16x32_f16 a[68:71], v[148:151], v[48:51], a[68:71]
	s_waitcnt lgkmcnt(4)
	v_mfma_f32_16x16x32_f16 a[84:87], v[156:159], v[48:51], a[84:87]
	s_waitcnt lgkmcnt(2)
	v_mfma_f32_16x16x32_f16 a[100:103], v[164:167], v[48:51], a[100:103]
	s_waitcnt lgkmcnt(1)
	v_mfma_f32_16x16x32_f16 a[116:119], v[172:175], v[48:51], a[116:119]
	v_add_f32_e32 v48, 0, v80
	v_add_f32_e32 v48, v81, v48
	v_add_f32_e32 v48, v82, v48
	v_add_f32_e32 v48, v83, v48
	v_add_f32_e32 v48, v108, v48
	v_add_f32_e32 v48, v109, v48
	v_add_f32_e32 v48, v110, v48
	v_add_f32_e32 v48, v111, v48
	v_add_f32_e32 v48, v112, v48
	v_add_f32_e32 v48, v113, v48
	v_add_f32_e32 v48, v114, v48
	v_add_f32_e32 v48, v137, v48
	v_add_f32_e32 v48, v138, v48
	v_add_f32_e32 v48, v139, v48
	v_add_f32_e32 v48, v140, v48
	v_add_f32_e32 v48, v141, v48
	v_add_f32_e32 v237, v48, v237
	v_add_f32_e32 v48, 0, v115
	v_add_f32_e32 v48, v116, v48
	v_add_f32_e32 v48, v117, v48
	v_add_f32_e32 v48, v118, v48
	v_add_f32_e32 v48, v119, v48
	v_add_f32_e32 v48, v120, v48
	v_add_f32_e32 v48, v121, v48
	v_add_f32_e32 v48, v122, v48
	v_add_f32_e32 v48, v123, v48
	v_add_f32_e32 v48, v129, v48
	v_add_f32_e32 v48, v130, v48
	v_add_f32_e32 v48, v131, v48
	v_add_f32_e32 v48, v132, v48
	v_add_f32_e32 v48, v133, v48
	v_add_f32_e32 v48, v134, v48
	v_add_f32_e32 v48, v135, v48
	v_mfma_f32_16x16x32_f16 a[64:67], v[148:151], v[56:59], a[64:67]
	v_add_f32_e32 v240, v48, v240
	v_add_f32_e32 v48, 0, v124
	v_add_f32_e32 v48, v125, v48
	v_mfma_f32_16x16x32_f16 a[76:79], v[156:159], v[56:59], a[76:79]
	v_add_f32_e32 v48, v126, v48
	v_add_f32_e32 v48, v127, v48
	v_add_f32_e32 v48, v104, v48
	v_mfma_f32_16x16x32_f16 a[92:95], v[164:167], v[56:59], a[92:95]
	v_add_f32_e32 v48, v105, v48
	v_add_f32_e32 v48, v106, v48
	v_add_f32_e32 v48, v107, v48
	v_mfma_f32_16x16x32_f16 a[108:111], v[172:175], v[56:59], a[108:111]
	v_add_f32_e32 v56, 0, v88
	v_add_f32_e32 v56, v89, v56
	v_add_f32_e32 v56, v90, v56
	v_add_f32_e32 v56, v91, v56
	v_mfma_f32_16x16x32_f16 a[40:43], v[178:181], v[60:63], a[40:43]
	v_add_f32_e32 v56, v92, v56
	v_add_f32_e32 v56, v93, v56
	v_add_f32_e32 v56, v94, v56
	v_mfma_f32_16x16x32_f16 a[48:51], v[178:181], v[52:55], a[48:51]
	v_add_f32_e32 v56, v95, v56
	v_add_f32_e32 v56, v96, v56
	v_add_f32_e32 v48, v84, v48
	v_mfma_f32_16x16x32_f16 a[56:59], v[178:181], v[68:71], a[56:59]
	v_add_f32_e32 v56, v97, v56
	v_add_f32_e32 v48, v85, v48
	v_add_f32_e32 v56, v98, v56
	v_mfma_f32_16x16x32_f16 a[60:63], v[178:181], v[76:79], a[60:63]
	ds_read2_b64 v[178:181], v136 offset0:104 offset1:108
	v_add_f32_e32 v48, v86, v48
	v_add_f32_e32 v56, v99, v56
	v_mfma_f32_16x16x32_f16 a[72:75], v[148:151], v[64:67], a[72:75]
	v_add_f32_e32 v48, v87, v48
	v_add_f32_e32 v56, v100, v56
	v_add_f32_e32 v48, v142, v48
	v_mfma_f32_16x16x32_f16 a[88:91], v[156:159], v[64:67], a[88:91]
	v_add_f32_e32 v56, v101, v56
	v_add_f32_e32 v48, v143, v48
	v_add_f32_e32 v56, v102, v56
	v_mfma_f32_16x16x32_f16 a[104:107], v[164:167], v[64:67], a[104:107]
	v_add_f32_e32 v48, v144, v48
	v_add_f32_e32 v56, v103, v56
	v_add_f32_e32 v48, v145, v48
	v_mfma_f32_16x16x32_f16 a[120:123], v[172:175], v[64:67], a[120:123]
	v_add_f32_e32 v236, v56, v236
	v_add_f32_e32 v235, v48, v235
	s_waitcnt lgkmcnt(0)
	v_mfma_f32_16x16x32_f16 a[80:83], v[148:151], v[72:75], a[80:83]
	s_barrier
; DI f4 mfma16(h8 a, h8 b, f4 c) { return __builtin_amdgcn_mfma_f32_16x16x32_f16(a, b, c, 0, 0, 0); }
; template <int DQK, bool BIAS>
; __device__ __forceinline__ void attn_pass(const hf* __restrict__ Q, int ldq, const hf* __restrict__ Kp, int ldk, const hf* __restrict__ VT,
;                                           int s0, int L, int q0, float scale_l2, const float* sBias, f4 (&oacc)[8][4], char* smem) {
;     ...
;       for (int nq = 0; nq < 4; ++nq)
; #pragma unroll
;         for (int m4 = 0; m4 < 4; ++m4) {
;           oacc[mh * 4 + m4][nq] = mfma16(vf[m4][0], pf[nq][0], oacc[mh * 4 + m4][nq]);
;           oacc[mh * 4 + m4][nq] = mfma16(vf[m4][1], pf[nq][1], oacc[mh * 4 + m4][nq]);
;         }
;     }
;     __syncthreads();
	v_mov_b32_e32 v242, v128
	v_mov_b32_e32 v243, v176
	v_mov_b32_e32 v244, v192
	v_mov_b32_e32 v225, v241
	s_mov_b32 s19, s14
	v_mfma_f32_16x16x32_f16 a[96:99], v[156:159], v[72:75], a[96:99]
	v_mfma_f32_16x16x32_f16 a[112:115], v[164:167], v[72:75], a[112:115]
	v_mfma_f32_16x16x32_f16 a[124:127], v[172:175], v[72:75], a[124:127]
	v_mfma_f32_16x16x32_f16 a[64:67], v[152:155], v[60:63], a[64:67]
	v_mfma_f32_16x16x32_f16 a[76:79], v[160:163], v[60:63], a[76:79]
	v_mfma_f32_16x16x32_f16 a[92:95], v[168:171], v[60:63], a[92:95]
	v_mfma_f32_16x16x32_f16 a[108:111], v[178:181], v[60:63], a[108:111]
	v_mfma_f32_16x16x32_f16 a[68:71], v[152:155], v[52:55], a[68:71]
	v_mfma_f32_16x16x32_f16 a[84:87], v[160:163], v[52:55], a[84:87]
	v_mfma_f32_16x16x32_f16 a[100:103], v[168:171], v[52:55], a[100:103]
	v_mfma_f32_16x16x32_f16 a[116:119], v[178:181], v[52:55], a[116:119]
	v_mfma_f32_16x16x32_f16 a[72:75], v[152:155], v[68:71], a[72:75]
	v_mfma_f32_16x16x32_f16 a[88:91], v[160:163], v[68:71], a[88:91]
	v_mfma_f32_16x16x32_f16 a[104:107], v[168:171], v[68:71], a[104:107]
	v_mfma_f32_16x16x32_f16 a[120:123], v[178:181], v[68:71], a[120:123]
	v_mfma_f32_16x16x32_f16 a[80:83], v[152:155], v[76:79], a[80:83]
	v_mfma_f32_16x16x32_f16 a[96:99], v[160:163], v[76:79], a[96:99]
	v_mfma_f32_16x16x32_f16 a[112:115], v[168:171], v[76:79], a[112:115]
	v_mfma_f32_16x16x32_f16 a[124:127], v[178:181], v[76:79], a[124:127]
	s_cbranch_scc1 .LBB0_1994
	s_branch .LBB0_1982
